# bundle: persistent packed row-sum pair + hoisted V addresses in the latent diff loop, NA score copies only on the non-local path, packed accumulator zeroing
# speedup vs baseline: 1.0004x; 1.0004x over previous
; DI int crow(int i, int h) { return (i & 3) + 8 * (i >> 2) + 4 * h; }
; DI f32x16 mfma32(bf8 a, bf8 b, f32x16 c) { return __builtin_amdgcn_mfma_f32_32x32x16_bf16(a, b, c, 0, 0, 0); }
; template <int DV, int MODE>
; DI void attn_item(const AttnArgs& a, char* smem) {
;     ...
;     bool active = true;
;     int kr = 0;
;     const bool local = (MODE == 2) && (tt < a.n0);
;     if (local) { kr = a.us + tt; active = (kr >= rsw) && (kr < rsw + 8); }
;     if (active) {
;       f32x16 s[2];
; #pragma unroll
;       for (int kb = 0; kb < 2; ++kb) {
; #pragma unroll
;         for (int i = 0; i < 16; ++i) s[kb][i] = 0.f;
; #pragma unroll
;         for (int ks = 0; ks < 4; ++ks) {
;           const bf8 kf = *(const bf8*)(Ks + (kb * 32 + r) * 72 + ks * 16 + h * 8);
;           s[kb] = mfma32(kf, qf[ks], s[kb]);
;         }
;       }
;       constexpr float SC = 0.125f * LOG2E;
;       float mx = -INFINITY;
;       if (local) {
; #pragma unroll
;         for (int kb = 0; kb < 2; ++kb)
; #pragma unroll
;           for (int i = 0; i < 16; ++i) {
;             const int kc = kb * 32 + crow(i, h);
;             const bool ok = (kc >= cs) && (kc < cs + 16);
;             const int dc = kc - qc + 15;
;             const int dr = kr - rq + 7;
;             const float bias = rpbS[dr * 32 + (ok ? dc : 0)];
;             const float v = ok ? (s[kb][i] + bias * (1.f / SC)) : -INFINITY;
;             s[kb][i] = v;
;             mx = fmaxf(mx, v);
;           }
;       } else {
; #pragma unroll
;         for (int kb = 0; kb < 2; ++kb)
; #pragma unroll
;           for (int i = 0; i < 16; i += 2) mx = fmaxf(fmaxf(mx, s[kb][i]), s[kb][i + 1]);
;       }
.LBB0_473:
	s_cmp_lt_i32 s72, s76
	s_cselect_b64 s[82:83], -1, 0
	s_cmp_ge_i32 s72, s76
	s_cselect_b64 s[10:11], -1, 0
	s_add_i32 s72, s0, s72
	v_cmp_ge_i32_e32 vcc, s72, v135
	v_cmp_lt_i32_e64 s[72:73], s72, v93
	s_and_b64 s[72:73], vcc, s[72:73]
	s_or_b64 s[10:11], s[10:11], s[72:73]
	s_andn2_b64 vcc, exec, s[10:11]
	s_cbranch_vccnz .LBB0_545
	v_add_u32_e32 v110, v0, v136
	ds_read_b128 v[34:37], v110
	ds_read_b128 v[98:101], v110 offset:32
	ds_read_b128 v[50:53], v110 offset:4608
	ds_read_b128 v[102:105], v110 offset:4640
	s_mov_b64 s[10:11], -1
	s_and_b64 vcc, exec, s[82:83]
	s_waitcnt lgkmcnt(1)
	v_mfma_f32_32x32x16_bf16 v[50:65], v[50:53], v[66:69], 0
	s_waitcnt lgkmcnt(0)
	v_mfma_f32_32x32x16_bf16 v[50:65], v[102:105], v[70:73], v[50:65]
	ds_read_b128 v[102:105], v110 offset:4672
	ds_read_b128 v[106:109], v110 offset:4704
	v_mfma_f32_32x32x16_bf16 v[34:49], v[34:37], v[66:69], 0
	s_waitcnt lgkmcnt(1)
	v_mfma_f32_32x32x16_bf16 v[50:65], v[102:105], v[74:77], v[50:65]
	v_mfma_f32_32x32x16_bf16 v[34:49], v[98:101], v[70:73], v[34:49]
	s_waitcnt lgkmcnt(0)
	v_mfma_f32_32x32x16_bf16 v[50:65], v[106:109], v[78:81], v[50:65]
	ds_read_b128 v[102:105], v110 offset:64
	ds_read_b128 v[106:109], v110 offset:96
	s_waitcnt lgkmcnt(1)
	v_mfma_f32_32x32x16_bf16 v[34:49], v[102:105], v[74:77], v[34:49]
	s_nop 7
	s_waitcnt lgkmcnt(0)
	v_mfma_f32_32x32x16_bf16 v[34:49], v[106:109], v[78:81], v[34:49]
	s_nop 2
	s_cbranch_vccz .LBB0_540
	v_mov_b32_e32 v253, 0xff800000
	ds_read_b32 v237, v138
	ds_read_b32 v238, v138 offset:4
	ds_read_b32 v239, v138 offset:8
	ds_read_b32 v240, v138 offset:12
	ds_read_b32 v241, v138 offset:32
	ds_read_b32 v242, v138 offset:36
	ds_read_b32 v243, v138 offset:40
	ds_read_b32 v244, v138 offset:44
	ds_read_b32 v245, v138 offset:64
	ds_read_b32 v246, v138 offset:68
	ds_read_b32 v247, v138 offset:72
	ds_read_b32 v248, v138 offset:76
	ds_read_b32 v249, v138 offset:96
	ds_read_b32 v250, v138 offset:100
	ds_read_b32 v251, v138 offset:104
	ds_read_b32 v252, v138 offset:108
	s_waitcnt lgkmcnt(15)
	v_fmamk_f32 v237, v237, 0x40b17218, v34
	v_cndmask_b32_e64 v98, v253, v237, s[36:37]
	s_waitcnt lgkmcnt(14)
	v_fmamk_f32 v238, v238, 0x40b17218, v35
	v_cndmask_b32_e64 v99, v253, v238, s[40:41]
	s_waitcnt lgkmcnt(13)
	v_fmamk_f32 v239, v239, 0x40b17218, v36
	v_cndmask_b32_e64 v100, v253, v239, s[42:43]
	s_waitcnt lgkmcnt(12)
	v_fmamk_f32 v240, v240, 0x40b17218, v37
	v_cndmask_b32_e64 v101, v253, v240, s[44:45]
	s_waitcnt lgkmcnt(11)
	v_fmamk_f32 v241, v241, 0x40b17218, v38
	v_cndmask_b32_e64 v102, v253, v241, s[46:47]
	s_waitcnt lgkmcnt(10)
	v_fmamk_f32 v242, v242, 0x40b17218, v39
	v_cndmask_b32_e64 v103, v253, v242, s[48:49]
	s_waitcnt lgkmcnt(9)
	v_fmamk_f32 v243, v243, 0x40b17218, v40
	v_cndmask_b32_e64 v104, v253, v243, s[50:51]
	s_waitcnt lgkmcnt(8)
	v_fmamk_f32 v244, v244, 0x40b17218, v41
	v_cndmask_b32_e64 v105, v253, v244, s[52:53]
	s_waitcnt lgkmcnt(7)
	v_fmamk_f32 v245, v245, 0x40b17218, v42
	v_cndmask_b32_e64 v106, v253, v245, s[12:13]
	s_waitcnt lgkmcnt(6)
	v_fmamk_f32 v246, v246, 0x40b17218, v43
	v_cndmask_b32_e64 v107, v253, v246, s[16:17]
	s_waitcnt lgkmcnt(5)
	v_fmamk_f32 v247, v247, 0x40b17218, v44
	v_cndmask_b32_e64 v108, v253, v247, s[18:19]
	s_waitcnt lgkmcnt(4)
	v_fmamk_f32 v248, v248, 0x40b17218, v45
	v_cndmask_b32_e64 v109, v253, v248, s[86:87]
	s_waitcnt lgkmcnt(3)
	v_fmamk_f32 v249, v249, 0x40b17218, v46
	v_cndmask_b32_e64 v110, v253, v249, s[78:79]
	s_waitcnt lgkmcnt(2)
	v_fmamk_f32 v250, v250, 0x40b17218, v47
	v_cndmask_b32_e64 v111, v253, v250, s[96:97]
	s_waitcnt lgkmcnt(1)
	v_fmamk_f32 v251, v251, 0x40b17218, v48
	v_cndmask_b32_e64 v112, v253, v251, s[92:93]
	s_waitcnt lgkmcnt(0)
	v_fmamk_f32 v252, v252, 0x40b17218, v49
	v_cndmask_b32_e64 v113, v253, v252, s[94:95]
	ds_read_b32 v237, v138 offset:128
	ds_read_b32 v238, v138 offset:132
	ds_read_b32 v239, v138 offset:136
	ds_read_b32 v240, v138 offset:140
	ds_read_b32 v241, v138 offset:160
	ds_read_b32 v242, v138 offset:164
	ds_read_b32 v243, v138 offset:168
	ds_read_b32 v244, v138 offset:172
	ds_read_b32 v245, v138 offset:192
	ds_read_b32 v246, v138 offset:196
	ds_read_b32 v247, v138 offset:200
	ds_read_b32 v248, v138 offset:204
	ds_read_b32 v249, v138 offset:224
	ds_read_b32 v250, v138 offset:228
	ds_read_b32 v251, v138 offset:232
	ds_read_b32 v252, v138 offset:236
	s_waitcnt lgkmcnt(15)
	v_fmamk_f32 v237, v237, 0x40b17218, v50
	v_cndmask_b32_e64 v114, v253, v237, s[22:23]
	s_waitcnt lgkmcnt(14)
	v_fmamk_f32 v238, v238, 0x40b17218, v51
	v_cndmask_b32_e64 v115, v253, v238, s[26:27]
	s_waitcnt lgkmcnt(13)
	v_fmamk_f32 v239, v239, 0x40b17218, v52
	v_cndmask_b32_e64 v116, v253, v239, s[2:3]
	s_waitcnt lgkmcnt(12)
	v_fmamk_f32 v240, v240, 0x40b17218, v53
	v_cndmask_b32_e64 v117, v253, v240, s[28:29]
	s_waitcnt lgkmcnt(11)
	v_fmamk_f32 v241, v241, 0x40b17218, v54
	v_cndmask_b32_e64 v118, v253, v241, s[74:75]
	s_waitcnt lgkmcnt(10)
	v_fmamk_f32 v242, v242, 0x40b17218, v55
	v_cndmask_b32_e64 v119, v253, v242, s[14:15]
	s_waitcnt lgkmcnt(9)
	v_fmamk_f32 v243, v243, 0x40b17218, v56
	v_cndmask_b32_e64 v120, v253, v243, s[70:71]
	s_waitcnt lgkmcnt(8)
	v_fmamk_f32 v244, v244, 0x40b17218, v57
	v_cndmask_b32_e64 v121, v253, v244, s[8:9]
	s_waitcnt lgkmcnt(7)
	v_fmamk_f32 v245, v245, 0x40b17218, v58
	v_cndmask_b32_e64 v122, v253, v245, s[54:55]
	s_waitcnt lgkmcnt(6)
	v_fmamk_f32 v246, v246, 0x40b17218, v59
	v_cndmask_b32_e64 v123, v253, v246, s[56:57]
	s_waitcnt lgkmcnt(5)
	v_fmamk_f32 v247, v247, 0x40b17218, v60
	v_cndmask_b32_e64 v124, v253, v247, s[58:59]
	s_waitcnt lgkmcnt(4)
	v_fmamk_f32 v248, v248, 0x40b17218, v61
	v_cndmask_b32_e64 v125, v253, v248, s[60:61]
	s_waitcnt lgkmcnt(3)
	v_fmamk_f32 v249, v249, 0x40b17218, v62
	v_cndmask_b32_e64 v126, v253, v249, s[62:63]
	s_waitcnt lgkmcnt(2)
	v_fmamk_f32 v250, v250, 0x40b17218, v63
	v_cndmask_b32_e64 v127, v253, v250, s[64:65]
	s_waitcnt lgkmcnt(1)
	v_fmamk_f32 v251, v251, 0x40b17218, v64
	v_cndmask_b32_e64 v128, v253, v251, s[66:67]
	s_waitcnt lgkmcnt(0)
	v_fmamk_f32 v252, v252, 0x40b17218, v65
	v_cndmask_b32_e64 v129, v253, v252, s[68:69]
	v_max3_f32 v141, v98, s33, v99
	v_max3_f32 v141, v141, v100, v101
	v_max3_f32 v141, v141, v102, v103
	v_max3_f32 v141, v141, v104, v105
	v_max3_f32 v141, v141, v106, v107
	v_max3_f32 v141, v141, v108, v109
	v_max3_f32 v141, v141, v110, v111
	v_max3_f32 v141, v141, v112, v113
	v_max3_f32 v141, v141, v114, v115
	v_max3_f32 v141, v141, v116, v117
	v_max3_f32 v141, v141, v118, v119
	v_max3_f32 v141, v141, v120, v121
	v_max3_f32 v141, v141, v122, v123
	v_max3_f32 v141, v141, v124, v125
	v_max3_f32 v141, v141, v126, v127
	v_max3_f32 v141, v141, v128, v129
	s_mov_b64 s[10:11], 0
; template <int DV, int MODE>
; DI void attn_item(const AttnArgs& a, char* smem) {
;     ...
;       } else {
; #pragma unroll
;         for (int kb = 0; kb < 2; ++kb)
; #pragma unroll
;           for (int i = 0; i < 16; i += 2) mx = fmaxf(fmaxf(mx, s[kb][i]), s[kb][i + 1]);
;       }
.LBB0_540:
	s_and_b64 vcc, exec, s[10:11]
	s_cbranch_vccz .LBB0_542
	v_mov_b32_e32 v129, v65
	v_mov_b32_e32 v128, v64
	v_mov_b32_e32 v127, v63
	v_mov_b32_e32 v126, v62
	v_mov_b32_e32 v125, v61
	v_mov_b32_e32 v124, v60
	v_mov_b32_e32 v123, v59
	v_mov_b32_e32 v122, v58
	v_mov_b32_e32 v121, v57
	v_mov_b32_e32 v120, v56
	v_mov_b32_e32 v119, v55
	v_mov_b32_e32 v118, v54
	v_mov_b32_e32 v117, v53
	v_mov_b32_e32 v116, v52
	v_mov_b32_e32 v115, v51
	v_mov_b32_e32 v114, v50
	v_mov_b32_e32 v113, v49
	v_mov_b32_e32 v112, v48
	v_mov_b32_e32 v111, v47
	v_mov_b32_e32 v110, v46
	v_mov_b32_e32 v109, v45
	v_mov_b32_e32 v108, v44
	v_mov_b32_e32 v107, v43
	v_mov_b32_e32 v106, v42
	v_mov_b32_e32 v105, v41
	v_mov_b32_e32 v104, v40
	v_mov_b32_e32 v103, v39
	v_mov_b32_e32 v102, v38
	v_mov_b32_e32 v101, v37
	v_mov_b32_e32 v100, v36
	v_mov_b32_e32 v99, v35
	v_mov_b32_e32 v98, v34
	v_max3_f32 v34, v34, s33, v35
	v_max3_f32 v34, v34, v36, v37
	v_max3_f32 v34, v34, v38, v39
	v_max3_f32 v34, v34, v40, v41
	v_max3_f32 v34, v34, v42, v43
	v_max3_f32 v34, v34, v44, v45
	v_max3_f32 v34, v34, v46, v47
	v_max3_f32 v34, v34, v48, v49
	v_max3_f32 v34, v34, v50, v51
	v_max3_f32 v34, v34, v52, v53
	v_max3_f32 v34, v34, v54, v55
	v_max3_f32 v34, v34, v56, v57
	v_max3_f32 v34, v34, v58, v59
	v_max3_f32 v34, v34, v60, v61
	v_max3_f32 v34, v34, v62, v63
	v_max3_f32 v141, v34, v64, v65

; template <int DV, int MODE>
; DI void attn_item(const AttnArgs& a, char* smem) {
;     ...
;   const int qrow = (MODE == 1) ? ((w & 3) * 32 + r) : (w * 32 + r);
;   const int qcoff = (MODE == 1) ? ((w >> 2) * 64) : 0;
;   u16* qp = a.qo + (size_t)qrow * 1024;
;   bf8 qf[4];
; #pragma unroll
;   for (int ks = 0; ks < 4; ++ks) qf[ks] = *(const bf8*)(qp + qcoff + ks * 16 + h * 8);
;   const u16* Ks = (MODE == 1 && (w >> 2)) ? Ks2 : Ks1;
;   int rq = 0, qc = 0, cs = 0, rsw = 0;
;   if (MODE == 2) {
;     __syncthreads();
;     for (int e = t; e < 15 * 32; e += NTHR) {
;       const int dr = e >> 5, dc = e & 31;
;       rpbS[e] = (dc < 31) ? a.rpb[dr * 31 + dc] * LOG2E : 0.f;
;     }
;     rq = a.rq0 + (w >> 1);
;     qc = (w & 1) * 32 + r;
;     cs = qc - 8; cs = cs < 0 ? 0 : (cs > 48 ? 48 : cs);
;     rsw = rq - 4; rsw = rsw < 0 ? 0 : (rsw > 24 ? 24 : rsw);
;   }
;   f32x16 O[NDV];
; #pragma unroll
;   for (int d = 0; d < NDV; ++d)
; #pragma unroll
;     for (int i = 0; i < 16; ++i) O[d][i] = 0.f;
;   float m = -1e30f, lsum = 0.f;
;   u32x4 rk1, rk2, rv[NVL];
;   const int srow = t >> 3, sch = t & 7;
;     ...
;   if (nt > 0) ATTN_FETCH(0)
; DI void phase_attn(const Params& p, int l, char* smem) {
;     ...
;       a.k2 = nullptr; a.rpb = nullptr; a.rq0 = 0; a.us = 0; a.lam = lam; a.oml = oml; a.subln = p.diff_subln + li * 128;
;       if (id < 1024) {
;         const int x = id & 7, q = id >> 3, qb = q & 15, g = (q >> 4) * 8 + x;
;         const int b = g >> 2, j = g & 3;
;         a.qo = QO + (size_t)(b * 2048 + qb * 128) * 1024 + 512 + j * 128;
;         a.k1 = Kb + ((size_t)b * 16 + 8 + 2 * j) * T * 64;
;         a.k2 = Kb + ((size_t)b * 16 + 8 + 2 * j + 1) * T * 64;
;         a.vt = VT + ((size_t)b * 1024 + 512 + j * 128) * T;
;         a.s0 = 0; a.n0 = 32; a.n1 = 4;
;         attn_item<128, 1>(a, smem);
.LBB0_551:
	s_andn2_b64 vcc, exec, s[2:3]
	s_cbranch_vccnz .LBB0_433
	s_ashr_i32 s2, s39, 4
	s_and_b32 s0, s39, 4
	s_and_b32 s2, s2, -8
	s_or_b32 s0, s2, s0
	s_lshl_b32 s3, s39, 4
	s_ashr_i32 s2, s0, 2
	s_lshl_b32 s0, s0, 9
	s_and_b32 s3, s3, 0x780
	s_or_b32 s8, s0, s3
	s_ashr_i32 s9, s8, 31
	s_and_b32 s12, s39, 3
	s_lshl_b64 s[8:9], s[8:9], 11
	s_add_u32 s0, s20, s8
	s_addc_u32 s3, s21, s9
	s_lshl_b32 s14, s12, 7
	s_lshl_b32 s8, s12, 8
	s_add_u32 s8, s0, s8
	s_addc_u32 s9, s3, 0
	s_ashr_i32 s3, s2, 31
	s_lshl_b64 s[10:11], s[2:3], 4
	s_lshl_b32 s0, s12, 1
	s_or_b32 s0, s10, s0
	s_mul_i32 s10, s11, 0x48000
	s_mul_hi_u32 s11, s0, 0x48000
	s_add_i32 s11, s11, s10
	s_mul_i32 s0, s0, 0x48000
	v_readlane_b32 s12, v235, 50
	v_readlane_b32 s13, v235, 51
	s_add_u32 s0, s12, s0
	s_addc_u32 s13, s13, s11
	s_add_u32 s10, s0, 0x240000
	s_addc_u32 s11, s13, 0
	s_add_u32 s12, s0, 0x288000
	s_addc_u32 s13, s13, 0
	s_lshl_b64 s[2:3], s[2:3], 10
	s_or_b32 s0, s2, s14
	s_mul_i32 s2, s3, 0x1200
	s_mul_hi_u32 s3, s0, 0x1200
	s_add_i32 s3, s3, s2
	s_mulk_i32 s0, 0x1200
	v_readlane_b32 s14, v235, 48
	v_readlane_b32 s15, v235, 49
	s_add_u32 s14, s14, s0
	v_mov_b32 v8, v163
	s_addc_u32 s15, s15, s3
	v_readfirstlane_b32 s0, v8
	s_ashr_i32 s2, s0, 6
	s_lshl_b32 s3, s2, 5
	v_and_b32_e32 v135, 31, v8
	s_and_b32 s3, s3, 0x60
	v_or_b32_e32 v0, s3, v135
	s_ashr_i32 s3, s0, 2
	s_and_b32 s16, s3, 0xffffffc0
	v_lshlrev_b32_e32 v0, 11, v0
	v_bfe_u32 v150, v8, 5, 1
	v_lshl_add_u64 v[132:133], s[8:9], 0, v[0:1]
	s_ashr_i32 s17, s16, 31
	v_lshl_add_u64 v[2:3], s[16:17], 1, v[132:133]
	v_lshlrev_b32_e32 v0, 4, v150
	v_ashrrev_i32_e32 v136, 3, v8
	v_lshl_add_u64 v[2:3], v[2:3], 0, v[0:1]
	v_ashrrev_i32_e32 v137, 31, v136
	global_load_dwordx4 v[98:101], v[2:3], off offset:1024
	global_load_dwordx4 v[102:105], v[2:3], off offset:1056
	global_load_dwordx4 v[106:109], v[2:3], off offset:1088
	global_load_dwordx4 v[110:113], v[2:3], off offset:1120
	v_lshlrev_b64 v[2:3], 7, v[136:137]
	v_lshlrev_b32_e32 v6, 4, v8
	v_lshl_add_u64 v[4:5], s[10:11], 0, v[2:3]
	v_and_b32_e32 v6, 0x70, v6
	v_mov_b32_e32 v7, v1
	v_lshl_add_u64 v[2:3], s[12:13], 0, v[2:3]
	v_lshl_add_u64 v[4:5], v[4:5], 0, v[6:7]
	v_lshl_add_u64 v[2:3], v[2:3], 0, v[6:7]
	global_load_dwordx4 v[114:117], v[4:5], off
	global_load_dwordx4 v[118:121], v[2:3], off
	v_lshl_add_u64 v[2:3], s[14:15], 0, v[6:7]
	s_mov_b64 s[8:9], 0x240000
	v_lshl_add_u64 v[138:139], v[2:3], 0, s[8:9]
	v_mad_i64_i32 v[2:3], s[8:9], v136, s77, v[138:139]
	v_add_u32_e32 v9, 64, v136
	v_mad_i64_i32 v[4:5], s[8:9], v9, s77, v[138:139]
	global_load_dwordx4 v[122:125], v[2:3], off
	global_load_dwordx4 v[126:129], v[4:5], off
	s_cmpk_lt_u32 s0, 0x100
	v_and_b32_e32 v2, 63, v8
	s_cselect_b32 s14, 0, 0x2400
	v_lshlrev_b32_e32 v134, 3, v150
	v_mul_lo_u32 v3, v136, s78
	v_or_b32_e32 v18, s14, v0
	v_lshlrev_b32_e32 v2, 2, v2
	v_mul_u32_u24_e32 v19, 0x90, v135
	v_mov_b32_e32 v16, v1
	v_mov_b32_e32 v17, v1
	v_mad_i64_i32 v[142:143], s[8:9], v9, s77, 0
	v_add_u32_e32 v151, v6, v3
	v_xor_b32_e32 v137, 0x80, v2
	v_lshl_add_u64 v[144:145], s[10:11], 0, v[6:7]
	v_lshl_add_u64 v[146:147], s[12:13], 0, v[6:7]
	v_mov_b32_e32 v2, v1
	v_mov_b32_e32 v3, v1
	v_mov_b32_e32 v4, v1
	v_mov_b32_e32 v5, v1
	v_mov_b32_e32 v6, v1
	v_mov_b32_e32 v8, v1
	v_mov_b32_e32 v9, v1
	v_mov_b32_e32 v10, v1
	v_mov_b32_e32 v11, v1
	v_mov_b32_e32 v12, v1
	v_mov_b32_e32 v13, v1
	v_mov_b32_e32 v14, v1
	v_mov_b32_e32 v15, v1
	v_add_u32_e32 v153, v18, v19
	v_add_u32_e32 v154, v134, v19
	v_mov_b64_e32 v[32:33], v[16:17]
	v_mov_b64_e32 v[48:49], v[16:17]
	v_mov_b64_e32 v[64:65], v[16:17]
	s_mov_b32 s3, 0
	v_mad_i64_i32 v[140:141], s[8:9], v136, s77, 0
	s_mov_b32 s0, 64
	v_mov_b32_e32 v152, 0
	v_mov_b32_e32 v155, 0xf149f2ca
	v_mov_b64_e32 v[30:31], v[14:15]
	v_mov_b64_e32 v[28:29], v[12:13]
	v_mov_b64_e32 v[26:27], v[10:11]
	v_mov_b64_e32 v[24:25], v[8:9]
	v_mov_b64_e32 v[22:23], v[6:7]
	v_mov_b64_e32 v[20:21], v[4:5]
	v_mov_b64_e32 v[18:19], v[2:3]
	v_mov_b64_e32 v[46:47], v[14:15]
	v_mov_b64_e32 v[44:45], v[12:13]
	v_mov_b64_e32 v[42:43], v[10:11]
	v_mov_b64_e32 v[40:41], v[8:9]
	v_mov_b64_e32 v[38:39], v[6:7]
	v_mov_b64_e32 v[36:37], v[4:5]
	v_mov_b64_e32 v[34:35], v[2:3]
	v_mov_b64_e32 v[62:63], v[14:15]
	v_mov_b64_e32 v[60:61], v[12:13]
	v_mov_b64_e32 v[58:59], v[10:11]
	v_mov_b64_e32 v[56:57], v[8:9]
	v_mov_b64_e32 v[54:55], v[6:7]
	v_mov_b64_e32 v[52:53], v[4:5]
	v_mov_b64_e32 v[50:51], v[2:3]
	v_add_u32_e32 v237, 0x4800, v154
	v_add_u32_e32 v250, 0x5800, v154
	v_add_u32_e32 v251, 0x6800, v154
	v_add_u32_e32 v160, 0x7800, v154
	v_mov_b32_e32 v168, 0
	v_mov_b32_e32 v169, 0
	s_branch .LBB0_554
; DI unsigned pack2(float a, float b) { f2 v = {a, b}; bf2 r = __builtin_convertvector(v, bf2); return __builtin_bit_cast(unsigned, r); }
; DI f32x16 mfma32(bf8 a, bf8 b, f32x16 c) { return __builtin_amdgcn_mfma_f32_32x32x16_bf16(a, b, c, 0, 0, 0); }
; DI float ex2(float x) { return __builtin_amdgcn_exp2f(x); }
; template <int DV, int MODE>
; DI void attn_item(const AttnArgs& a, char* smem) {
;     ...
; #pragma unroll
;       for (int kb = 0; kb < 2; ++kb)
; #pragma unroll
;         for (int i = 0; i < 16; i += 2) {
;           f32x2n v = {s[kb][i], s[kb][i + 1]};
;           v = v * f32x2n{SC, SC} - f32x2n{mn, mn};
;           const float p0 = ex2(v.x), p1 = ex2(v.y);
;           s[kb][i] = p0; s[kb][i + 1] = p1;
;           ps0 += p0; ps1 += p1;
;         }
;       if (resc) {
;         const float alpha = ex2(m - mn);
;         m = mn;
;         lsum *= alpha;
; #pragma unroll
;         for (int d = 0; d < NDV; ++d)
; #pragma unroll
;           for (int i = 0; i < 16; ++i) O[d][i] *= alpha;
;       }
;       lsum += ps0 + ps1;
; #pragma unroll
;       for (int kb = 0; kb < 2; ++kb)
; #pragma unroll
;         for (int s2 = 0; s2 < 2; ++s2) {
;           u32x4 pk;
;           pk.x = pack2(s[kb][s2 * 8 + 0], s[kb][s2 * 8 + 1]);
;           pk.y = pack2(s[kb][s2 * 8 + 2], s[kb][s2 * 8 + 3]);
;           pk.z = pack2(s[kb][s2 * 8 + 4], s[kb][s2 * 8 + 5]);
;           pk.w = pack2(s[kb][s2 * 8 + 6], s[kb][s2 * 8 + 7]);
;           const bf8 pf = __builtin_bit_cast(bf8, pk);
; #pragma unroll
;           for (int d = 0; d < NDV; ++d) {
;             const u16* vp = Vs + (d * 32 + r) * 72 + kb * 32 + s2 * 16 + 4 * h;
;             u32x4 vv;
;             const u32x2 lo = *(const u32x2*)(vp);
;             const u32x2 hi = *(const u32x2*)(vp + 8);
;             vv.x = lo.x; vv.y = lo.y; vv.z = hi.x; vv.w = hi.y;
;             O[d] = mfma32(__builtin_bit_cast(bf8, vv), pf, O[d]);
;           }
;         }
.LBB0_553:
	s_add_i32 s3, s3, 1
	s_add_i32 s0, s0, 64
	ds_read2_b64 v[238:241], v237 offset1:2
	ds_read2_b64 v[242:245], v250 offset0:64 offset1:66
	ds_read2_b64 v[246:249], v251 offset0:128 offset1:130
	ds_read2_b64 v[252:255], v160 offset0:192 offset1:194
	v_pk_fma_f32 v[82:83], v[82:83], s[24:25], v[148:149] op_sel_hi:[1,0,0] neg_lo:[0,0,1] neg_hi:[0,0,1]
	v_pk_fma_f32 v[84:85], v[84:85], s[24:25], v[148:149] op_sel_hi:[1,0,0] neg_lo:[0,0,1] neg_hi:[0,0,1]
	v_pk_fma_f32 v[86:87], v[86:87], s[24:25], v[148:149] op_sel_hi:[1,0,0] neg_lo:[0,0,1] neg_hi:[0,0,1]
	v_pk_fma_f32 v[88:89], v[88:89], s[24:25], v[148:149] op_sel_hi:[1,0,0] neg_lo:[0,0,1] neg_hi:[0,0,1]
	v_exp_f32_e32 v82, v82
	v_exp_f32_e32 v83, v83
	v_exp_f32_e32 v84, v84
	v_exp_f32_e32 v85, v85
	v_exp_f32_e32 v86, v86
	v_exp_f32_e32 v87, v87
	v_exp_f32_e32 v88, v88
	v_exp_f32_e32 v89, v89
	v_cvt_pk_bf16_f32 v156, v82, v83
	v_cvt_pk_bf16_f32 v157, v84, v85
	v_cvt_pk_bf16_f32 v158, v86, v87
	v_cvt_pk_bf16_f32 v159, v88, v89
	v_pk_add_f32 v[168:169], v[82:83], v[168:169]
	v_pk_add_f32 v[168:169], v[84:85], v[168:169]
	v_pk_add_f32 v[168:169], v[86:87], v[168:169]
	v_pk_add_f32 v[168:169], v[88:89], v[168:169]
	s_waitcnt lgkmcnt(3)
	v_mfma_f32_32x32x16_bf16 v[50:65], v[238:241], v[156:159], v[50:65]
	ds_read2_b64 v[238:241], v237 offset0:4 offset1:6
	v_pk_fma_f32 v[90:91], v[90:91], s[24:25], v[148:149] op_sel_hi:[1,0,0] neg_lo:[0,0,1] neg_hi:[0,0,1]
	v_pk_fma_f32 v[92:93], v[92:93], s[24:25], v[148:149] op_sel_hi:[1,0,0] neg_lo:[0,0,1] neg_hi:[0,0,1]
	v_pk_fma_f32 v[94:95], v[94:95], s[24:25], v[148:149] op_sel_hi:[1,0,0] neg_lo:[0,0,1] neg_hi:[0,0,1]
	v_pk_fma_f32 v[96:97], v[96:97], s[24:25], v[148:149] op_sel_hi:[1,0,0] neg_lo:[0,0,1] neg_hi:[0,0,1]
	v_exp_f32_e32 v90, v90
	v_exp_f32_e32 v91, v91
	s_waitcnt lgkmcnt(3)
	v_mfma_f32_32x32x16_bf16 v[34:49], v[242:245], v[156:159], v[34:49]
	ds_read2_b64 v[242:245], v250 offset0:68 offset1:70
	v_exp_f32_e32 v92, v92
	v_exp_f32_e32 v93, v93
	v_exp_f32_e32 v94, v94
	v_exp_f32_e32 v95, v95
	v_exp_f32_e32 v96, v96
	v_exp_f32_e32 v97, v97
	s_waitcnt lgkmcnt(3)
	v_mfma_f32_32x32x16_bf16 v[18:33], v[246:249], v[156:159], v[18:33]
	ds_read2_b64 v[246:249], v251 offset0:132 offset1:134
	v_cvt_pk_bf16_f32 v164, v90, v91
	v_cvt_pk_bf16_f32 v165, v92, v93
	v_cvt_pk_bf16_f32 v166, v94, v95
	v_cvt_pk_bf16_f32 v167, v96, v97
	s_waitcnt lgkmcnt(3)
	v_mfma_f32_32x32x16_bf16 v[2:17], v[252:255], v[156:159], v[2:17]
	ds_read2_b64 v[252:255], v160 offset0:196 offset1:198
	v_pk_add_f32 v[168:169], v[90:91], v[168:169]
	v_pk_add_f32 v[168:169], v[92:93], v[168:169]
	v_pk_add_f32 v[168:169], v[94:95], v[168:169]
	v_pk_add_f32 v[168:169], v[96:97], v[168:169]
	s_waitcnt lgkmcnt(3)
	v_mfma_f32_32x32x16_bf16 v[50:65], v[238:241], v[164:167], v[50:65]
	ds_read2_b64 v[238:241], v237 offset0:8 offset1:10
	v_pk_fma_f32 v[66:67], v[66:67], s[24:25], v[148:149] op_sel_hi:[1,0,0] neg_lo:[0,0,1] neg_hi:[0,0,1]
	v_pk_fma_f32 v[68:69], v[68:69], s[24:25], v[148:149] op_sel_hi:[1,0,0] neg_lo:[0,0,1] neg_hi:[0,0,1]
	v_pk_fma_f32 v[70:71], v[70:71], s[24:25], v[148:149] op_sel_hi:[1,0,0] neg_lo:[0,0,1] neg_hi:[0,0,1]
	v_pk_fma_f32 v[72:73], v[72:73], s[24:25], v[148:149] op_sel_hi:[1,0,0] neg_lo:[0,0,1] neg_hi:[0,0,1]
	v_exp_f32_e32 v66, v66
	v_exp_f32_e32 v67, v67
	s_waitcnt lgkmcnt(3)
	v_mfma_f32_32x32x16_bf16 v[34:49], v[242:245], v[164:167], v[34:49]
	ds_read2_b64 v[242:245], v250 offset0:72 offset1:74
	v_exp_f32_e32 v68, v68
	v_exp_f32_e32 v69, v69
	v_exp_f32_e32 v70, v70
	v_exp_f32_e32 v71, v71
	v_exp_f32_e32 v72, v72
	v_exp_f32_e32 v73, v73
	s_waitcnt lgkmcnt(3)
	v_mfma_f32_32x32x16_bf16 v[18:33], v[246:249], v[164:167], v[18:33]
	ds_read2_b64 v[246:249], v251 offset0:136 offset1:138
	v_cvt_pk_bf16_f32 v156, v66, v67
	v_cvt_pk_bf16_f32 v157, v68, v69
	v_cvt_pk_bf16_f32 v158, v70, v71
	v_cvt_pk_bf16_f32 v159, v72, v73
	s_waitcnt lgkmcnt(3)
	v_mfma_f32_32x32x16_bf16 v[2:17], v[252:255], v[164:167], v[2:17]
	ds_read2_b64 v[252:255], v160 offset0:200 offset1:202
	v_pk_add_f32 v[168:169], v[66:67], v[168:169]
	v_pk_add_f32 v[168:169], v[68:69], v[168:169]
	v_pk_add_f32 v[168:169], v[70:71], v[168:169]
	v_pk_add_f32 v[168:169], v[72:73], v[168:169]
	s_waitcnt lgkmcnt(3)
	v_mfma_f32_32x32x16_bf16 v[50:65], v[238:241], v[156:159], v[50:65]
	ds_read2_b64 v[238:241], v237 offset0:12 offset1:14
	v_pk_fma_f32 v[74:75], v[74:75], s[24:25], v[148:149] op_sel_hi:[1,0,0] neg_lo:[0,0,1] neg_hi:[0,0,1]
	v_pk_fma_f32 v[76:77], v[76:77], s[24:25], v[148:149] op_sel_hi:[1,0,0] neg_lo:[0,0,1] neg_hi:[0,0,1]
	v_pk_fma_f32 v[78:79], v[78:79], s[24:25], v[148:149] op_sel_hi:[1,0,0] neg_lo:[0,0,1] neg_hi:[0,0,1]
	v_pk_fma_f32 v[80:81], v[80:81], s[24:25], v[148:149] op_sel_hi:[1,0,0] neg_lo:[0,0,1] neg_hi:[0,0,1]
	v_exp_f32_e32 v74, v74
	v_exp_f32_e32 v75, v75
	s_waitcnt lgkmcnt(3)
	v_mfma_f32_32x32x16_bf16 v[34:49], v[242:245], v[156:159], v[34:49]
	ds_read2_b64 v[242:245], v250 offset0:76 offset1:78
	v_exp_f32_e32 v76, v76
	v_exp_f32_e32 v77, v77
	v_exp_f32_e32 v78, v78
	v_exp_f32_e32 v79, v79
	v_exp_f32_e32 v80, v80
	v_exp_f32_e32 v81, v81
	s_waitcnt lgkmcnt(3)
	v_mfma_f32_32x32x16_bf16 v[18:33], v[246:249], v[156:159], v[18:33]
	ds_read2_b64 v[246:249], v251 offset0:140 offset1:142
	v_cvt_pk_bf16_f32 v164, v74, v75
	v_cvt_pk_bf16_f32 v165, v76, v77
	v_cvt_pk_bf16_f32 v166, v78, v79
	v_cvt_pk_bf16_f32 v167, v80, v81
	s_waitcnt lgkmcnt(3)
	v_mfma_f32_32x32x16_bf16 v[2:17], v[252:255], v[156:159], v[2:17]
	ds_read2_b64 v[252:255], v160 offset0:204 offset1:206
	v_pk_add_f32 v[168:169], v[74:75], v[168:169]
	v_pk_add_f32 v[168:169], v[76:77], v[168:169]
	v_pk_add_f32 v[168:169], v[78:79], v[168:169]
	v_pk_add_f32 v[168:169], v[80:81], v[168:169]
	s_waitcnt lgkmcnt(3)
	v_mfma_f32_32x32x16_bf16 v[50:65], v[238:241], v[164:167], v[50:65]
	s_waitcnt lgkmcnt(2)
	v_mfma_f32_32x32x16_bf16 v[34:49], v[242:245], v[164:167], v[34:49]
	s_waitcnt lgkmcnt(1)
	v_mfma_f32_32x32x16_bf16 v[18:33], v[246:249], v[164:167], v[18:33]
	s_waitcnt lgkmcnt(0)
	v_mfma_f32_32x32x16_bf16 v[2:17], v[252:255], v[164:167], v[2:17]
	s_cmp_eq_u32 s3, 36
	s_cbranch_scc1 .LBB0_558

; DI float ex2(float x) { return __builtin_amdgcn_exp2f(x); }
; DI float shx(float v, int lane, int mask) { return __int_as_float(__builtin_amdgcn_ds_bpermute((lane ^ mask) << 2, __float_as_int(v))); }
; template <int DV, int MODE>
; DI void attn_item(const AttnArgs& a, char* smem) {
;     ...
;       mx = fmaxf(mx, shx(mx, lane, 32)) * SC;
;       const float mn = fmaxf(m, mx);
;       const bool resc = __builtin_amdgcn_ballot_w64(mn != m) != 0ull;
;       float ps0 = 0.f, ps1 = 0.f;
; #pragma unroll
;       for (int kb = 0; kb < 2; ++kb)
; #pragma unroll
;         for (int i = 0; i < 16; i += 2) {
;           f32x2n v = {s[kb][i], s[kb][i + 1]};
;           v = v * f32x2n{SC, SC} - f32x2n{mn, mn};
;           const float p0 = ex2(v.x), p1 = ex2(v.y);
;           s[kb][i] = p0; s[kb][i + 1] = p1;
;           ps0 += p0; ps1 += p1;
;         }
;       if (resc) {
;         const float alpha = ex2(m - mn);
;         m = mn;
;         lsum *= alpha;
; #pragma unroll
;         for (int d = 0; d < NDV; ++d)
; #pragma unroll
;           for (int i = 0; i < 16; ++i) O[d][i] *= alpha;
;       }
.Llz_8:
	ds_bpermute_b32 v156, v137, v148
	s_waitcnt lgkmcnt(0)
	v_max_f32_e32 v156, v156, v156
	v_max_f32_e32 v148, v148, v156
	v_mul_f32_e32 v148, 0x3e38aa3b, v148
	v_max_f32_e32 v156, v155, v155
	v_max_f32_e32 v148, v156, v148
	v_cmp_neq_f32_e32 vcc, v148, v155
	s_cbranch_vccz .LBB0_553
	v_sub_f32_e32 v155, v155, v148
	v_exp_f32_e32 v156, v155
	v_mov_b32_e32 v155, v148
	v_pk_mul_f32 v[64:65], v[64:65], v[156:157] op_sel_hi:[1,0]
	v_pk_mul_f32 v[62:63], v[62:63], v[156:157] op_sel_hi:[1,0]
	v_pk_mul_f32 v[60:61], v[60:61], v[156:157] op_sel_hi:[1,0]
	v_pk_mul_f32 v[58:59], v[58:59], v[156:157] op_sel_hi:[1,0]
	v_pk_mul_f32 v[56:57], v[56:57], v[156:157] op_sel_hi:[1,0]
	v_pk_mul_f32 v[54:55], v[54:55], v[156:157] op_sel_hi:[1,0]
	v_pk_mul_f32 v[52:53], v[52:53], v[156:157] op_sel_hi:[1,0]
	v_pk_mul_f32 v[50:51], v[50:51], v[156:157] op_sel_hi:[1,0]
	v_pk_mul_f32 v[48:49], v[48:49], v[156:157] op_sel_hi:[1,0]
	v_pk_mul_f32 v[46:47], v[46:47], v[156:157] op_sel_hi:[1,0]
	v_pk_mul_f32 v[44:45], v[44:45], v[156:157] op_sel_hi:[1,0]
	v_pk_mul_f32 v[42:43], v[42:43], v[156:157] op_sel_hi:[1,0]
	v_pk_mul_f32 v[40:41], v[40:41], v[156:157] op_sel_hi:[1,0]
	v_pk_mul_f32 v[38:39], v[38:39], v[156:157] op_sel_hi:[1,0]
	v_pk_mul_f32 v[36:37], v[36:37], v[156:157] op_sel_hi:[1,0]
	v_pk_mul_f32 v[34:35], v[34:35], v[156:157] op_sel_hi:[1,0]
	v_pk_mul_f32 v[32:33], v[32:33], v[156:157] op_sel_hi:[1,0]
	v_pk_mul_f32 v[30:31], v[30:31], v[156:157] op_sel_hi:[1,0]
	v_pk_mul_f32 v[28:29], v[28:29], v[156:157] op_sel_hi:[1,0]
	v_pk_mul_f32 v[26:27], v[26:27], v[156:157] op_sel_hi:[1,0]
	v_pk_mul_f32 v[24:25], v[24:25], v[156:157] op_sel_hi:[1,0]
	v_pk_mul_f32 v[22:23], v[22:23], v[156:157] op_sel_hi:[1,0]
	v_pk_mul_f32 v[20:21], v[20:21], v[156:157] op_sel_hi:[1,0]
	v_pk_mul_f32 v[18:19], v[18:19], v[156:157] op_sel_hi:[1,0]
	v_pk_mul_f32 v[16:17], v[16:17], v[156:157] op_sel_hi:[1,0]
	v_pk_mul_f32 v[14:15], v[14:15], v[156:157] op_sel_hi:[1,0]
	v_pk_mul_f32 v[12:13], v[12:13], v[156:157] op_sel_hi:[1,0]
	v_pk_mul_f32 v[10:11], v[10:11], v[156:157] op_sel_hi:[1,0]
	v_pk_mul_f32 v[8:9], v[8:9], v[156:157] op_sel_hi:[1,0]
	v_pk_mul_f32 v[6:7], v[6:7], v[156:157] op_sel_hi:[1,0]
	v_pk_mul_f32 v[4:5], v[4:5], v[156:157] op_sel_hi:[1,0]
	v_pk_mul_f32 v[2:3], v[2:3], v[156:157] op_sel_hi:[1,0]
	v_mul_f32_e32 v152, v152, v156
	v_pk_mul_f32 v[168:169], v[168:169], v[156:157] op_sel_hi:[1,0]
	s_branch .LBB0_553
; DI unsigned pack2(float a, float b) { f2 v = {a, b}; bf2 r = __builtin_convertvector(v, bf2); return __builtin_bit_cast(unsigned, r); }
; DI int crow(int i, int h) { return (i & 3) + 8 * (i >> 2) + 4 * h; }
; DI float shx(float v, int lane, int mask) { return __int_as_float(__builtin_amdgcn_ds_bpermute((lane ^ mask) << 2, __float_as_int(v))); }
; template <int DV, int MODE>
; DI void attn_item(const AttnArgs& a, char* smem) {
;     ...
;   const float ltot = lsum + shx(lsum, lane, 32);
;   const float inv = 1.f / ltot;
;   if (MODE != 1) {
; #pragma unroll
;     for (int d = 0; d < NDV; ++d)
; #pragma unroll
;       for (int ig = 0; ig < 4; ++ig) {
;         u32x2 o;
;         o.x = pack2(O[d][ig * 4 + 0] * inv, O[d][ig * 4 + 1] * inv);
;         o.y = pack2(O[d][ig * 4 + 2] * inv, O[d][ig * 4 + 3] * inv);
;         *(u32x2*)(qp + d * 32 + ig * 8 + h * 4) = o;
;       }
;   } else {
;     float* comb = (float*)smem;
;     __syncthreads();
;     if (w >= 4) {
; #pragma unroll
;       for (int d = 0; d < NDV; ++d)
; #pragma unroll
;         for (int i = 0; i < 16; ++i) comb[((w - 4) * 128 + d * 32 + crow(i, h)) * 32 + r] = O[d][i] * inv;
;     }
;     __syncthreads();
.LBB0_558:
	v_add_f32_e32 v168, v168, v169
	v_add_f32_e32 v152, v168, v152
	ds_bpermute_b32 v66, v137, v152
	s_cmp_lt_i32 s2, 4
	s_waitcnt lgkmcnt(0)
	s_barrier
	v_add_f32_e32 v66, v152, v66
	v_div_scale_f32 v67, s[8:9], v66, v66, 1.0
	v_rcp_f32_e32 v68, v67
	v_div_scale_f32 v69, vcc, 1.0, v66, 1.0
	v_fma_f32 v70, -v67, v68, 1.0
	v_fmac_f32_e32 v68, v70, v68
	v_mul_f32_e32 v70, v69, v68
	v_fma_f32 v71, -v67, v70, v69
	v_fmac_f32_e32 v70, v71, v68
	v_fma_f32 v67, -v67, v70, v69
	v_div_fmas_f32 v67, v67, v68, v70
	v_div_fixup_f32 v72, v67, v66, 1.0
	v_lshlrev_b32_e32 v66, 2, v135
	v_lshlrev_b32_e32 v67, 9, v150
	s_cbranch_scc1 .LBB0_560
	s_lshl_b32 s0, s2, 14
	v_or3_b32 v69, v66, v67, s0
	v_mul_f32_e32 v68, v50, v72
	v_add_u32_e32 v70, 0xffff0000, v69
	ds_write_b32 v70, v68
	v_mul_f32_e32 v68, v51, v72
	v_add_u32_e32 v70, 0xffff0080, v69
	ds_write_b32 v70, v68
	v_mul_f32_e32 v68, v52, v72
	v_add_u32_e32 v70, 0xffff0100, v69
	ds_write_b32 v70, v68
	v_mul_f32_e32 v68, v53, v72
	v_add_u32_e32 v70, 0xffff0180, v69
	ds_write_b32 v70, v68
	v_mul_f32_e32 v68, v54, v72
	v_add_u32_e32 v70, 0xffff0400, v69
	ds_write_b32 v70, v68
	v_mul_f32_e32 v68, v55, v72
	v_add_u32_e32 v70, 0xffff0480, v69
	ds_write_b32 v70, v68
	v_mul_f32_e32 v68, v56, v72
	v_add_u32_e32 v70, 0xffff0500, v69
	ds_write_b32 v70, v68
	v_mul_f32_e32 v68, v57, v72
	v_add_u32_e32 v70, 0xffff0580, v69
	ds_write_b32 v70, v68
	v_mul_f32_e32 v68, v58, v72
	v_add_u32_e32 v70, 0xffff0800, v69
	ds_write_b32 v70, v68
	v_mul_f32_e32 v68, v59, v72
	v_add_u32_e32 v70, 0xffff0880, v69
	ds_write_b32 v70, v68
	v_mul_f32_e32 v68, v60, v72
	v_add_u32_e32 v70, 0xffff0900, v69
	ds_write_b32 v70, v68
	v_mul_f32_e32 v68, v61, v72
	v_add_u32_e32 v70, 0xffff0980, v69
	ds_write_b32 v70, v68
	v_mul_f32_e32 v68, v62, v72
	v_add_u32_e32 v70, 0xffff0c00, v69
	ds_write_b32 v70, v68
	v_mul_f32_e32 v68, v63, v72
	v_add_u32_e32 v70, 0xffff0c80, v69
	ds_write_b32 v70, v68
	v_mul_f32_e32 v68, v64, v72
	v_add_u32_e32 v70, 0xffff0d00, v69
	ds_write_b32 v70, v68
	v_mul_f32_e32 v68, v65, v72
	v_add_u32_e32 v70, 0xffff0d80, v69
	ds_write_b32 v70, v68
	v_mul_f32_e32 v68, v34, v72
	v_add_u32_e32 v70, 0xffff1000, v69
	ds_write_b32 v70, v68
	v_mul_f32_e32 v68, v35, v72
	v_add_u32_e32 v70, 0xffff1080, v69
	ds_write_b32 v70, v68
	v_mul_f32_e32 v68, v36, v72
	v_add_u32_e32 v70, 0xffff1100, v69
	ds_write_b32 v70, v68
	v_mul_f32_e32 v68, v37, v72
	v_add_u32_e32 v70, 0xffff1180, v69
	ds_write_b32 v70, v68
	v_mul_f32_e32 v68, v38, v72
	v_add_u32_e32 v70, 0xffff1400, v69
	ds_write_b32 v70, v68
	v_mul_f32_e32 v68, v39, v72
	v_add_u32_e32 v70, 0xffff1480, v69
	ds_write_b32 v70, v68
	v_mul_f32_e32 v68, v40, v72
	v_add_u32_e32 v70, 0xffff1500, v69
	ds_write_b32 v70, v68
	v_mul_f32_e32 v68, v41, v72
	v_add_u32_e32 v70, 0xffff1580, v69
	ds_write_b32 v70, v68
	v_mul_f32_e32 v68, v42, v72
	v_add_u32_e32 v70, 0xffff1800, v69
	ds_write_b32 v70, v68
	v_mul_f32_e32 v68, v43, v72
	v_add_u32_e32 v70, 0xffff1880, v69
	ds_write_b32 v70, v68
	v_mul_f32_e32 v68, v44, v72
	v_add_u32_e32 v70, 0xffff1900, v69
	ds_write_b32 v70, v68
	v_mul_f32_e32 v68, v45, v72
	v_add_u32_e32 v70, 0xffff1980, v69
	ds_write_b32 v70, v68
	v_mul_f32_e32 v68, v46, v72
	v_add_u32_e32 v70, 0xffff1c00, v69
	ds_write_b32 v70, v68
	v_mul_f32_e32 v68, v47, v72
	v_add_u32_e32 v70, 0xffff1c80, v69
	ds_write_b32 v70, v68
	v_mul_f32_e32 v68, v48, v72
	v_add_u32_e32 v70, 0xffff1d00, v69
	ds_write_b32 v70, v68
	v_mul_f32_e32 v68, v49, v72
	v_add_u32_e32 v70, 0xffff1d80, v69
	ds_write_b32 v70, v68
	v_mul_f32_e32 v68, v18, v72
	v_add_u32_e32 v70, 0xffff2000, v69
	ds_write_b32 v70, v68
	v_mul_f32_e32 v68, v19, v72
	v_add_u32_e32 v70, 0xffff2080, v69
	ds_write_b32 v70, v68
	v_mul_f32_e32 v68, v20, v72
	v_add_u32_e32 v70, 0xffff2100, v69
	ds_write_b32 v70, v68
	v_mul_f32_e32 v68, v21, v72
	v_add_u32_e32 v70, 0xffff2180, v69
	ds_write_b32 v70, v68
	v_mul_f32_e32 v68, v22, v72
	v_add_u32_e32 v70, 0xffff2400, v69
	ds_write_b32 v70, v68
	v_mul_f32_e32 v68, v23, v72
	v_add_u32_e32 v70, 0xffff2480, v69
	ds_write_b32 v70, v68
	v_mul_f32_e32 v68, v24, v72
	v_add_u32_e32 v70, 0xffff2500, v69
	ds_write_b32 v70, v68
	v_mul_f32_e32 v68, v25, v72
	v_add_u32_e32 v70, 0xffff2580, v69
	ds_write_b32 v70, v68
	v_mul_f32_e32 v68, v26, v72
	v_add_u32_e32 v70, 0xffff2800, v69
	ds_write_b32 v70, v68
	v_mul_f32_e32 v68, v27, v72
	v_add_u32_e32 v70, 0xffff2880, v69
	ds_write_b32 v70, v68
	v_mul_f32_e32 v68, v28, v72
	v_add_u32_e32 v70, 0xffff2900, v69
	ds_write_b32 v70, v68
	v_mul_f32_e32 v68, v29, v72
	v_add_u32_e32 v70, 0xffff2980, v69
	ds_write_b32 v70, v68
	v_mul_f32_e32 v68, v30, v72
	v_add_u32_e32 v70, 0xffff2c00, v69
	ds_write_b32 v70, v68
	v_mul_f32_e32 v68, v31, v72
	v_add_u32_e32 v70, 0xffff2c80, v69
	ds_write_b32 v70, v68
	v_mul_f32_e32 v68, v32, v72
	v_add_u32_e32 v70, 0xffff2d00, v69
	ds_write_b32 v70, v68
	v_mul_f32_e32 v68, v33, v72
	v_add_u32_e32 v70, 0xffff2d80, v69
	ds_write_b32 v70, v68
	v_mul_f32_e32 v68, v2, v72
	v_add_u32_e32 v70, 0xffff3000, v69
	ds_write_b32 v70, v68
	v_mul_f32_e32 v68, v3, v72
	v_add_u32_e32 v70, 0xffff3080, v69
	ds_write_b32 v70, v68
	v_mul_f32_e32 v68, v4, v72
	v_add_u32_e32 v70, 0xffff3100, v69
	ds_write_b32 v70, v68
	v_mul_f32_e32 v68, v5, v72
	v_add_u32_e32 v70, 0xffff3180, v69
	ds_write_b32 v70, v68
	v_mul_f32_e32 v68, v6, v72
	v_add_u32_e32 v70, 0xffff3400, v69
	ds_write_b32 v70, v68
	v_mul_f32_e32 v68, v7, v72
	v_add_u32_e32 v70, 0xffff3480, v69
	ds_write_b32 v70, v68
	v_mul_f32_e32 v68, v8, v72
	v_add_u32_e32 v70, 0xffff3500, v69
	ds_write_b32 v70, v68
	v_mul_f32_e32 v68, v9, v72
	v_add_u32_e32 v70, 0xffff3580, v69
	ds_write_b32 v70, v68
	v_mul_f32_e32 v68, v10, v72
	v_add_u32_e32 v70, 0xffff3800, v69
	ds_write_b32 v70, v68
	v_mul_f32_e32 v68, v11, v72
	v_add_u32_e32 v70, 0xffff3880, v69
	ds_write_b32 v70, v68
	v_mul_f32_e32 v68, v12, v72
	v_add_u32_e32 v70, 0xffff3900, v69
	ds_write_b32 v70, v68
	v_mul_f32_e32 v68, v13, v72
	v_add_u32_e32 v70, 0xffff3980, v69
	ds_write_b32 v70, v68
	v_mul_f32_e32 v68, v14, v72
	v_add_u32_e32 v70, 0xffff3c00, v69
	ds_write_b32 v70, v68
	v_mul_f32_e32 v68, v15, v72
	v_add_u32_e32 v70, 0xffff3c80, v69
	ds_write_b32 v70, v68
	v_mul_f32_e32 v68, v16, v72
	v_add_u32_e32 v70, 0xffff3d00, v69
	ds_write_b32 v70, v68
	v_mul_f32_e32 v68, v17, v72
	v_add_u32_e32 v69, 0xffff3d80, v69
	ds_write_b32 v69, v68
